# row-norm loop: contiguous rows per wave, 16-byte write-through stores
# speedup vs baseline: 1.0232x; 1.0059x over previous
.LBB0_8:
	s_lshr_b32 s30, s10, 6
	s_lshl_b32 s2, s72, 3
	s_add_i32 s76, s30, s2
	s_lshl_b32 s78, s97, 3
	s_add_u32 s74, s88, 0x6000000
	s_addc_u32 s75, s89, 0
	s_cmp_lt_i32 s90, 1
	s_cselect_b64 s[2:3], -1, 0
	s_cmp_gt_i32 s91, 0
	s_cselect_b64 s[4:5], -1, 0
	s_and_b64 s[2:3], s[2:3], s[4:5]
	s_andn2_b64 vcc, exec, s[2:3]
	s_cbranch_vccnz .LBB0_74
	s_bitcmp0_b32 s10, 6
	s_cselect_b64 s[24:25], -1, 0
	s_cmp_lt_i32 s76, 0x8000
	v_mov_b32_e32 v0, v200
	s_cselect_b64 s[4:5], -1, 0
	s_and_b64 vcc, exec, s[24:25]
	v_and_b32_e32 v59, 63, v0
	v_cndmask_b32_e64 v0, 0, 1, s[4:5]
	v_cmp_ne_u32_e64 s[6:7], 1, v0
	s_cbranch_vccnz .LBB0_21
	s_and_b64 vcc, exec, s[6:7]
	s_cbranch_vccnz .LBB0_21
	s_waitcnt lgkmcnt(0)
	v_and_b32_e32 v147, 63, v200
	v_lshlrev_b32_e32 v144, 5, v147
	v_lshlrev_b32_e32 v145, 4, v147
	v_mov_b32_e32 v150, 0x358637bd
	v_readlane_b32 s8, v248, 2
	v_readlane_b32 s9, v248, 3
	v_readlane_b32 s16, v248, 6
	v_readlane_b32 s17, v248, 7
	s_mov_b32 s14, 0x3a800000
	s_mov_b32 s18, 0
	s_mov_b32 s12, 0
.Lrw_ra:
	s_add_i32 s18, s18, s78
	s_add_i32 s12, s12, 1
	s_cmp_lt_i32 s18, 0x8000
	s_cbranch_scc1 .Lrw_ra
	s_mul_i32 s4, s76, s12
	s_add_i32 s13, s4, s12
	s_min_i32 s13, s13, 0x8000
	s_mov_b32 s5, s4
	s_cmp_lt_i32 s4, s13
	s_cbranch_scc0 .LBB0_21
	s_lshr_b32 s19, s4, 20
	s_lshl_b32 s18, s4, 12
	s_add_u32 s8, s8, s18
	s_addc_u32 s9, s9, s19
	s_lshr_b32 s19, s4, 21
	s_lshl_b32 s18, s4, 11
	s_add_u32 s10, s74, s18
	s_addc_u32 s11, s75, s19
	global_load_dwordx4 v[128:131], v144, s[16:17]
	global_load_dwordx4 v[132:135], v144, s[16:17] offset:16
	global_load_dwordx4 v[136:139], v144, s[16:17] offset:2048
	global_load_dwordx4 v[140:143], v144, s[16:17] offset:2064
	global_load_dwordx4 v[64:67], v144, s[8:9] nt
	global_load_dwordx4 v[68:71], v144, s[8:9] offset:16 nt
	global_load_dwordx4 v[72:75], v144, s[8:9] offset:2048 nt
	global_load_dwordx4 v[76:79], v144, s[8:9] offset:2064 nt
	s_add_u32 s8, s8, 0x1000
	s_addc_u32 s9, s9, 0
	s_add_i32 s4, s4, 1
	s_cmp_lt_i32 s4, s13
	s_cbranch_scc0 .Lrw_filla
	global_load_dwordx4 v[80:83], v144, s[8:9] nt
	global_load_dwordx4 v[84:87], v144, s[8:9] offset:16 nt
	global_load_dwordx4 v[88:91], v144, s[8:9] offset:2048 nt
	global_load_dwordx4 v[92:95], v144, s[8:9] offset:2064 nt
	s_add_u32 s8, s8, 0x1000
	s_addc_u32 s9, s9, 0
	s_add_i32 s4, s4, 1
	s_cmp_lt_i32 s4, s13
	s_cbranch_scc0 .Lrw_filla
	global_load_dwordx4 v[96:99], v144, s[8:9] nt
	global_load_dwordx4 v[100:103], v144, s[8:9] offset:16 nt
	global_load_dwordx4 v[104:107], v144, s[8:9] offset:2048 nt
	global_load_dwordx4 v[108:111], v144, s[8:9] offset:2064 nt
	s_add_u32 s8, s8, 0x1000
	s_addc_u32 s9, s9, 0
	s_add_i32 s4, s4, 1
	s_cmp_lt_i32 s4, s13
	s_cbranch_scc0 .Lrw_filla
	global_load_dwordx4 v[112:115], v144, s[8:9] nt
	global_load_dwordx4 v[116:119], v144, s[8:9] offset:16 nt
	global_load_dwordx4 v[120:123], v144, s[8:9] offset:2048 nt
	global_load_dwordx4 v[124:127], v144, s[8:9] offset:2064 nt
	s_add_u32 s8, s8, 0x1000
	s_addc_u32 s9, s9, 0
	s_add_i32 s4, s4, 1

.Lrw_loopa:
	s_add_i32 s15, s5, 3
	s_cmp_lt_i32 s15, s13
	s_cbranch_scc1 .Lrw_f0a
	s_waitcnt vmcnt(0)
	s_branch .Lrw_c0a
.Lrw_f0a:
	s_cmp_eq_u32 s19, 1
	s_cbranch_scc1 .Lrw_g0a
	s_waitcnt vmcnt(18)
	s_branch .Lrw_c0a

.Lrw_c0a:
	v_mul_f32_e32 v146, v64, v64
	v_fmac_f32_e32 v146, v65, v65
	v_fmac_f32_e32 v146, v66, v66
	v_fmac_f32_e32 v146, v67, v67
	v_fmac_f32_e32 v146, v68, v68
	v_fmac_f32_e32 v146, v69, v69
	v_fmac_f32_e32 v146, v70, v70
	v_fmac_f32_e32 v146, v71, v71
	v_fmac_f32_e32 v146, v72, v72
	v_fmac_f32_e32 v146, v73, v73
	v_fmac_f32_e32 v146, v74, v74
	v_fmac_f32_e32 v146, v75, v75
	v_fmac_f32_e32 v146, v76, v76
	v_fmac_f32_e32 v146, v77, v77
	v_fmac_f32_e32 v146, v78, v78
	v_fmac_f32_e32 v146, v79, v79
	v_mul_f32_e32 v64, v64, v128
	v_mul_f32_e32 v65, v65, v129
	v_add_f32_dpp v146, v146, v146 quad_perm:[1,0,3,2] row_mask:0xf bank_mask:0xf
	v_mul_f32_e32 v66, v66, v130
	v_mul_f32_e32 v67, v67, v131
	v_add_f32_dpp v146, v146, v146 quad_perm:[2,3,0,1] row_mask:0xf bank_mask:0xf
	v_mul_f32_e32 v68, v68, v132
	v_mul_f32_e32 v69, v69, v133
	v_add_f32_dpp v146, v146, v146 row_ror:4 row_mask:0xf bank_mask:0xf
	v_mul_f32_e32 v70, v70, v134
	v_mul_f32_e32 v71, v71, v135
	v_add_f32_dpp v146, v146, v146 row_ror:8 row_mask:0xf bank_mask:0xf
	v_mul_f32_e32 v72, v72, v136
	v_mul_f32_e32 v73, v73, v137
	v_mov_b32_e32 v147, v146
	v_mul_f32_e32 v74, v74, v138
	v_mul_f32_e32 v75, v75, v139
	v_permlane16_swap_b32_e32 v146, v147
	v_add_f32_e32 v146, v146, v147
	v_mov_b32_e32 v147, v146
	v_mul_f32_e32 v76, v76, v140
	v_mul_f32_e32 v77, v77, v141
	v_permlane32_swap_b32_e32 v146, v147
	v_add_f32_e32 v146, v146, v147
	v_mul_f32_e32 v78, v78, v142
	v_mul_f32_e32 v79, v79, v143
	v_fma_f32 v146, v146, s14, v150
	v_rsq_f32_e32 v148, v146
	v_mul_f32_e32 v146, 0.5, v146
	s_nop 0
	v_mul_f32_e32 v149, v148, v148
	v_fma_f32 v149, -v146, v149, 0.5
	v_fmac_f32_e32 v148, v148, v149
	v_mul_f32_e32 v64, v64, v148
	v_mul_f32_e32 v65, v65, v148
	v_mul_f32_e32 v66, v66, v148
	v_mul_f32_e32 v67, v67, v148
	v_mul_f32_e32 v68, v68, v148
	v_mul_f32_e32 v69, v69, v148
	v_mul_f32_e32 v70, v70, v148
	v_mul_f32_e32 v71, v71, v148
	v_mul_f32_e32 v72, v72, v148
	v_mul_f32_e32 v73, v73, v148
	v_mul_f32_e32 v74, v74, v148
	v_mul_f32_e32 v75, v75, v148
	v_mul_f32_e32 v76, v76, v148
	v_mul_f32_e32 v77, v77, v148
	v_mul_f32_e32 v78, v78, v148
	v_mul_f32_e32 v79, v79, v148
	v_cvt_pk_bf16_f32 v64, v64, v65
	v_cvt_pk_bf16_f32 v65, v66, v67
	v_cvt_pk_bf16_f32 v66, v68, v69
	v_cvt_pk_bf16_f32 v67, v70, v71
	v_cvt_pk_bf16_f32 v72, v72, v73
	v_cvt_pk_bf16_f32 v73, v74, v75
	v_cvt_pk_bf16_f32 v74, v76, v77
	v_cvt_pk_bf16_f32 v75, v78, v79
	global_store_dwordx4 v145, v[64:67], s[10:11] sc1
	global_store_dwordx4 v145, v[72:75], s[10:11] offset:1024 sc1
	s_add_u32 s10, s10, 0x800
	s_addc_u32 s11, s11, 0
	s_cmp_lt_i32 s4, s13
	s_cbranch_scc0 .Lrw_nl0a
	global_load_dwordx4 v[64:67], v144, s[8:9] nt
	global_load_dwordx4 v[68:71], v144, s[8:9] offset:16 nt
	global_load_dwordx4 v[72:75], v144, s[8:9] offset:2048 nt
	global_load_dwordx4 v[76:79], v144, s[8:9] offset:2064 nt
	s_add_u32 s8, s8, 0x1000
	s_addc_u32 s9, s9, 0
	s_add_i32 s4, s4, 1
.Lrw_nl0a:
	s_add_i32 s5, s5, 1
	s_cmp_lt_i32 s5, s13
	s_cbranch_scc0 .LBB0_21
	s_add_i32 s15, s5, 3
	s_cmp_lt_i32 s15, s13
	s_cbranch_scc1 .Lrw_f1a
	s_waitcnt vmcnt(0)
	s_branch .Lrw_c1a

.Lrw_g1a:
	s_waitcnt vmcnt(14)
.Lrw_c1a:
	v_mul_f32_e32 v146, v80, v80
	v_fmac_f32_e32 v146, v81, v81
	v_fmac_f32_e32 v146, v82, v82
	v_fmac_f32_e32 v146, v83, v83
	v_fmac_f32_e32 v146, v84, v84
	v_fmac_f32_e32 v146, v85, v85
	v_fmac_f32_e32 v146, v86, v86
	v_fmac_f32_e32 v146, v87, v87
	v_fmac_f32_e32 v146, v88, v88
	v_fmac_f32_e32 v146, v89, v89
	v_fmac_f32_e32 v146, v90, v90
	v_fmac_f32_e32 v146, v91, v91
	v_fmac_f32_e32 v146, v92, v92
	v_fmac_f32_e32 v146, v93, v93
	v_fmac_f32_e32 v146, v94, v94
	v_fmac_f32_e32 v146, v95, v95
	v_mul_f32_e32 v80, v80, v128
	v_mul_f32_e32 v81, v81, v129
	v_add_f32_dpp v146, v146, v146 quad_perm:[1,0,3,2] row_mask:0xf bank_mask:0xf
	v_mul_f32_e32 v82, v82, v130
	v_mul_f32_e32 v83, v83, v131
	v_add_f32_dpp v146, v146, v146 quad_perm:[2,3,0,1] row_mask:0xf bank_mask:0xf
	v_mul_f32_e32 v84, v84, v132
	v_mul_f32_e32 v85, v85, v133
	v_add_f32_dpp v146, v146, v146 row_ror:4 row_mask:0xf bank_mask:0xf
	v_mul_f32_e32 v86, v86, v134
	v_mul_f32_e32 v87, v87, v135
	v_add_f32_dpp v146, v146, v146 row_ror:8 row_mask:0xf bank_mask:0xf
	v_mul_f32_e32 v88, v88, v136
	v_mul_f32_e32 v89, v89, v137
	v_mov_b32_e32 v147, v146
	v_mul_f32_e32 v90, v90, v138
	v_mul_f32_e32 v91, v91, v139
	v_permlane16_swap_b32_e32 v146, v147
	v_add_f32_e32 v146, v146, v147
	v_mov_b32_e32 v147, v146
	v_mul_f32_e32 v92, v92, v140
	v_mul_f32_e32 v93, v93, v141
	v_permlane32_swap_b32_e32 v146, v147
	v_add_f32_e32 v146, v146, v147
	v_mul_f32_e32 v94, v94, v142
	v_mul_f32_e32 v95, v95, v143
	v_fma_f32 v146, v146, s14, v150
	v_rsq_f32_e32 v148, v146
	v_mul_f32_e32 v146, 0.5, v146
	s_nop 0
	v_mul_f32_e32 v149, v148, v148
	v_fma_f32 v149, -v146, v149, 0.5
	v_fmac_f32_e32 v148, v148, v149
	v_mul_f32_e32 v80, v80, v148
	v_mul_f32_e32 v81, v81, v148
	v_mul_f32_e32 v82, v82, v148
	v_mul_f32_e32 v83, v83, v148
	v_mul_f32_e32 v84, v84, v148
	v_mul_f32_e32 v85, v85, v148
	v_mul_f32_e32 v86, v86, v148
	v_mul_f32_e32 v87, v87, v148
	v_mul_f32_e32 v88, v88, v148
	v_mul_f32_e32 v89, v89, v148
	v_mul_f32_e32 v90, v90, v148
	v_mul_f32_e32 v91, v91, v148
	v_mul_f32_e32 v92, v92, v148
	v_mul_f32_e32 v93, v93, v148
	v_mul_f32_e32 v94, v94, v148
	v_mul_f32_e32 v95, v95, v148
	v_cvt_pk_bf16_f32 v80, v80, v81
	v_cvt_pk_bf16_f32 v81, v82, v83
	v_cvt_pk_bf16_f32 v82, v84, v85
	v_cvt_pk_bf16_f32 v83, v86, v87
	v_cvt_pk_bf16_f32 v88, v88, v89
	v_cvt_pk_bf16_f32 v89, v90, v91
	v_cvt_pk_bf16_f32 v90, v92, v93
	v_cvt_pk_bf16_f32 v91, v94, v95
	global_store_dwordx4 v145, v[80:83], s[10:11] sc1
	global_store_dwordx4 v145, v[88:91], s[10:11] offset:1024 sc1
	s_add_u32 s10, s10, 0x800
	s_addc_u32 s11, s11, 0
	s_cmp_lt_i32 s4, s13
	s_cbranch_scc0 .Lrw_nl1a
	global_load_dwordx4 v[80:83], v144, s[8:9] nt
	global_load_dwordx4 v[84:87], v144, s[8:9] offset:16 nt
	global_load_dwordx4 v[88:91], v144, s[8:9] offset:2048 nt
	global_load_dwordx4 v[92:95], v144, s[8:9] offset:2064 nt
	s_add_u32 s8, s8, 0x1000
	s_addc_u32 s9, s9, 0
	s_add_i32 s4, s4, 1

.Lrw_c2a:
	v_mul_f32_e32 v146, v96, v96
	v_fmac_f32_e32 v146, v97, v97
	v_fmac_f32_e32 v146, v98, v98
	v_fmac_f32_e32 v146, v99, v99
	v_fmac_f32_e32 v146, v100, v100
	v_fmac_f32_e32 v146, v101, v101
	v_fmac_f32_e32 v146, v102, v102
	v_fmac_f32_e32 v146, v103, v103
	v_fmac_f32_e32 v146, v104, v104
	v_fmac_f32_e32 v146, v105, v105
	v_fmac_f32_e32 v146, v106, v106
	v_fmac_f32_e32 v146, v107, v107
	v_fmac_f32_e32 v146, v108, v108
	v_fmac_f32_e32 v146, v109, v109
	v_fmac_f32_e32 v146, v110, v110
	v_fmac_f32_e32 v146, v111, v111
	v_mul_f32_e32 v96, v96, v128
	v_mul_f32_e32 v97, v97, v129
	v_add_f32_dpp v146, v146, v146 quad_perm:[1,0,3,2] row_mask:0xf bank_mask:0xf
	v_mul_f32_e32 v98, v98, v130
	v_mul_f32_e32 v99, v99, v131
	v_add_f32_dpp v146, v146, v146 quad_perm:[2,3,0,1] row_mask:0xf bank_mask:0xf
	v_mul_f32_e32 v100, v100, v132
	v_mul_f32_e32 v101, v101, v133
	v_add_f32_dpp v146, v146, v146 row_ror:4 row_mask:0xf bank_mask:0xf
	v_mul_f32_e32 v102, v102, v134
	v_mul_f32_e32 v103, v103, v135
	v_add_f32_dpp v146, v146, v146 row_ror:8 row_mask:0xf bank_mask:0xf
	v_mul_f32_e32 v104, v104, v136
	v_mul_f32_e32 v105, v105, v137
	v_mov_b32_e32 v147, v146
	v_mul_f32_e32 v106, v106, v138
	v_mul_f32_e32 v107, v107, v139
	v_permlane16_swap_b32_e32 v146, v147
	v_add_f32_e32 v146, v146, v147
	v_mov_b32_e32 v147, v146
	v_mul_f32_e32 v108, v108, v140
	v_mul_f32_e32 v109, v109, v141
	v_permlane32_swap_b32_e32 v146, v147
	v_add_f32_e32 v146, v146, v147
	v_mul_f32_e32 v110, v110, v142
	v_mul_f32_e32 v111, v111, v143
	v_fma_f32 v146, v146, s14, v150
	v_rsq_f32_e32 v148, v146
	v_mul_f32_e32 v146, 0.5, v146
	s_nop 0
	v_mul_f32_e32 v149, v148, v148
	v_fma_f32 v149, -v146, v149, 0.5
	v_fmac_f32_e32 v148, v148, v149
	v_mul_f32_e32 v96, v96, v148
	v_mul_f32_e32 v97, v97, v148
	v_mul_f32_e32 v98, v98, v148
	v_mul_f32_e32 v99, v99, v148
	v_mul_f32_e32 v100, v100, v148
	v_mul_f32_e32 v101, v101, v148
	v_mul_f32_e32 v102, v102, v148
	v_mul_f32_e32 v103, v103, v148
	v_mul_f32_e32 v104, v104, v148
	v_mul_f32_e32 v105, v105, v148
	v_mul_f32_e32 v106, v106, v148
	v_mul_f32_e32 v107, v107, v148
	v_mul_f32_e32 v108, v108, v148
	v_mul_f32_e32 v109, v109, v148
	v_mul_f32_e32 v110, v110, v148
	v_mul_f32_e32 v111, v111, v148
	v_cvt_pk_bf16_f32 v96, v96, v97
	v_cvt_pk_bf16_f32 v97, v98, v99
	v_cvt_pk_bf16_f32 v98, v100, v101
	v_cvt_pk_bf16_f32 v99, v102, v103
	v_cvt_pk_bf16_f32 v104, v104, v105
	v_cvt_pk_bf16_f32 v105, v106, v107
	v_cvt_pk_bf16_f32 v106, v108, v109
	v_cvt_pk_bf16_f32 v107, v110, v111
	global_store_dwordx4 v145, v[96:99], s[10:11] sc1
	global_store_dwordx4 v145, v[104:107], s[10:11] offset:1024 sc1
	s_add_u32 s10, s10, 0x800
	s_addc_u32 s11, s11, 0
	s_cmp_lt_i32 s4, s13
	s_cbranch_scc0 .Lrw_nl2a
	global_load_dwordx4 v[96:99], v144, s[8:9] nt
	global_load_dwordx4 v[100:103], v144, s[8:9] offset:16 nt
	global_load_dwordx4 v[104:107], v144, s[8:9] offset:2048 nt
	global_load_dwordx4 v[108:111], v144, s[8:9] offset:2064 nt
	s_add_u32 s8, s8, 0x1000
	s_addc_u32 s9, s9, 0
	s_add_i32 s4, s4, 1

.Lrw_c3a:
	v_mul_f32_e32 v146, v112, v112
	v_fmac_f32_e32 v146, v113, v113
	v_fmac_f32_e32 v146, v114, v114
	v_fmac_f32_e32 v146, v115, v115
	v_fmac_f32_e32 v146, v116, v116
	v_fmac_f32_e32 v146, v117, v117
	v_fmac_f32_e32 v146, v118, v118
	v_fmac_f32_e32 v146, v119, v119
	v_fmac_f32_e32 v146, v120, v120
	v_fmac_f32_e32 v146, v121, v121
	v_fmac_f32_e32 v146, v122, v122
	v_fmac_f32_e32 v146, v123, v123
	v_fmac_f32_e32 v146, v124, v124
	v_fmac_f32_e32 v146, v125, v125
	v_fmac_f32_e32 v146, v126, v126
	v_fmac_f32_e32 v146, v127, v127
	v_mul_f32_e32 v112, v112, v128
	v_mul_f32_e32 v113, v113, v129
	v_add_f32_dpp v146, v146, v146 quad_perm:[1,0,3,2] row_mask:0xf bank_mask:0xf
	v_mul_f32_e32 v114, v114, v130
	v_mul_f32_e32 v115, v115, v131
	v_add_f32_dpp v146, v146, v146 quad_perm:[2,3,0,1] row_mask:0xf bank_mask:0xf
	v_mul_f32_e32 v116, v116, v132
	v_mul_f32_e32 v117, v117, v133
	v_add_f32_dpp v146, v146, v146 row_ror:4 row_mask:0xf bank_mask:0xf
	v_mul_f32_e32 v118, v118, v134
	v_mul_f32_e32 v119, v119, v135
	v_add_f32_dpp v146, v146, v146 row_ror:8 row_mask:0xf bank_mask:0xf
	v_mul_f32_e32 v120, v120, v136
	v_mul_f32_e32 v121, v121, v137
	v_mov_b32_e32 v147, v146
	v_mul_f32_e32 v122, v122, v138
	v_mul_f32_e32 v123, v123, v139
	v_permlane16_swap_b32_e32 v146, v147
	v_add_f32_e32 v146, v146, v147
	v_mov_b32_e32 v147, v146
	v_mul_f32_e32 v124, v124, v140
	v_mul_f32_e32 v125, v125, v141
	v_permlane32_swap_b32_e32 v146, v147
	v_add_f32_e32 v146, v146, v147
	v_mul_f32_e32 v126, v126, v142
	v_mul_f32_e32 v127, v127, v143
	v_fma_f32 v146, v146, s14, v150
	v_rsq_f32_e32 v148, v146
	v_mul_f32_e32 v146, 0.5, v146
	s_nop 0
	v_mul_f32_e32 v149, v148, v148
	v_fma_f32 v149, -v146, v149, 0.5
	v_fmac_f32_e32 v148, v148, v149
	v_mul_f32_e32 v112, v112, v148
	v_mul_f32_e32 v113, v113, v148
	v_mul_f32_e32 v114, v114, v148
	v_mul_f32_e32 v115, v115, v148
	v_mul_f32_e32 v116, v116, v148
	v_mul_f32_e32 v117, v117, v148
	v_mul_f32_e32 v118, v118, v148
	v_mul_f32_e32 v119, v119, v148
	v_mul_f32_e32 v120, v120, v148
	v_mul_f32_e32 v121, v121, v148
	v_mul_f32_e32 v122, v122, v148
	v_mul_f32_e32 v123, v123, v148
	v_mul_f32_e32 v124, v124, v148
	v_mul_f32_e32 v125, v125, v148
	v_mul_f32_e32 v126, v126, v148
	v_mul_f32_e32 v127, v127, v148
	v_cvt_pk_bf16_f32 v112, v112, v113
	v_cvt_pk_bf16_f32 v113, v114, v115
	v_cvt_pk_bf16_f32 v114, v116, v117
	v_cvt_pk_bf16_f32 v115, v118, v119
	v_cvt_pk_bf16_f32 v120, v120, v121
	v_cvt_pk_bf16_f32 v121, v122, v123
	v_cvt_pk_bf16_f32 v122, v124, v125
	v_cvt_pk_bf16_f32 v123, v126, v127
	global_store_dwordx4 v145, v[112:115], s[10:11] sc1
	global_store_dwordx4 v145, v[120:123], s[10:11] offset:1024 sc1
	s_add_u32 s10, s10, 0x800
	s_addc_u32 s11, s11, 0
	s_cmp_lt_i32 s4, s13
	s_cbranch_scc0 .Lrw_nl3a
	global_load_dwordx4 v[112:115], v144, s[8:9] nt
	global_load_dwordx4 v[116:119], v144, s[8:9] offset:16 nt
	global_load_dwordx4 v[120:123], v144, s[8:9] offset:2048 nt
	global_load_dwordx4 v[124:127], v144, s[8:9] offset:2064 nt
	s_add_u32 s8, s8, 0x1000
	s_addc_u32 s9, s9, 0
	s_add_i32 s4, s4, 1
.Lrw_nl3a:
	s_add_i32 s5, s5, 1
	s_cmp_lt_i32 s5, s13
	s_mov_b32 s19, 0
	s_cbranch_scc1 .Lrw_loopa

.LBB0_61:
	s_and_b64 vcc, exec, s[24:25]
	s_cbranch_vccz .LBB0_73
	s_and_b64 vcc, exec, s[6:7]
	s_cbranch_vccnz .LBB0_73
	s_waitcnt lgkmcnt(0)
	v_and_b32_e32 v147, 63, v200
	v_lshlrev_b32_e32 v144, 5, v147
	v_lshlrev_b32_e32 v145, 4, v147
	v_mov_b32_e32 v150, 0x358637bd
	v_readlane_b32 s8, v248, 2
	v_readlane_b32 s9, v248, 3
	v_readlane_b32 s16, v248, 6
	v_readlane_b32 s17, v248, 7
	s_mov_b32 s14, 0x3a800000
	s_mov_b32 s18, 0
	s_mov_b32 s12, 0
